# attention loop wave priority experiment 17b (a: no static prio, b: prio for waves 0-3 instead of 4-7)
# baseline (speedup 1.0000x reference)
; #define SLOAD(i, k0) do { sr_[i].vs0 = LD8(&Vh[(long)((k0) + sr) * LDK + sc]); sr_[i].vs1 = LD8(&Vh[(long)((k0) + 32 + sr) * LDK + sc]); \
;     sr_[i].ks0 = LD8(&Kh[(long)((k0) + sr) * LDK + sc]); sr_[i].ks1 = LD8(&Kh[(long)((k0) + 32 + sr) * LDK + sc]); } while (0)
; #define SWRITE(b, i) do { *(bf16x8*)((char*)V_lds + (b) * SHM_V + vst0) = sr_[i].vs0;          \
;     *(bf16x8*)((char*)V_lds + (b) * SHM_V + vst1) = sr_[i].vs1; int kc = sc * 2;               \
;     *(bf16x8*)((char*)K_lds + (b) * SHM_K + KSWZ(sr, kc)) = sr_[i].ks0;                       \
;     *(bf16x8*)((char*)K_lds + (b) * SHM_K + KSWZ(32 + sr, kc)) = sr_[i].ks1; } while (0)
; #define SWAIT() asm volatile("s_waitcnt vmcnt(4)" ::: "memory")
; __device__ __forceinline__ void attn_body(const bf16_t* __restrict__ Qb, const bf16_t* __restrict__ Kh, const bf16_t* __restrict__ Vh, const bf16_t* __restrict__ Zb, ...
;     ...
;     SLOAD(SE, 2 * KVBLK);
;     SWAIT(); SWRITE(1, SO); __syncthreads();
;     if (__builtin_amdgcn_readfirstlane(tid) >= 256) __builtin_amdgcn_s_setprio(1);
.LBB0_487:
	v_add_u32_e32 v32, 0x80, v186
	v_mad_i64_i32 v[32:33], s[42:43], v32, s31, 0
	v_add_u32_e32 v34, 0xa0, v186
	v_or_b32_e32 v32, v32, v198
	v_mad_i64_i32 v[34:35], s[42:43], v34, s31, 0
	v_lshl_add_u64 v[32:33], v[32:33], 1, s[20:21]
	v_or_b32_e32 v34, v34, v198
	v_lshl_add_u64 v[34:35], v[34:35], 1, s[20:21]
	global_load_dwordx4 v[144:147], v[32:33], off offset:2560
	global_load_dwordx4 v[148:151], v[32:33], off offset:2048
	global_load_dwordx4 v[156:159], v[34:35], off offset:2560
	global_load_dwordx4 v[152:155], v[34:35], off offset:2048
	s_waitcnt vmcnt(4)
	v_readfirstlane_b32 s23, v200
	v_ashrrev_i32_e32 v187, 31, v186
	s_cmpk_lt_i32 s23, 0x100
	ds_write_b128 v207, v[16:19] offset:16384
	ds_write_b128 v208, v[28:31] offset:16384
	ds_write_b128 v209, v[20:23] offset:49152
	ds_write_b128 v210, v[24:27] offset:49152
	s_waitcnt lgkmcnt(0)
	s_barrier
	s_cbranch_scc0 .LBB0_489
	s_setprio 1
